# RWKV step C: 4 contiguous columns per lane, b128 LDS reads/writes (24 -> 12 LDS instructions per chunk)
# baseline (speedup 1.0000x reference)
.LBB0_421:
	s_or_b64 exec, exec, s[18:19]
	s_mul_i32 s52, s36, 0x20800
	s_xor_b64 s[76:77], s[22:23], -1
	s_lshl_b64 s[18:19], s[52:53], 2
	s_add_u32 s18, s20, s18
	v_mov_b32_e32 v6, 0xc200
	v_mov_b32_e32 v7, 0xb000
	s_addc_u32 s19, s21, s19
	v_cndmask_b32_e64 v6, v6, v7, s[16:17]
	s_lshl_b32 s16, s34, 1
	s_add_u32 s20, s20, s16
	s_addc_u32 s21, s21, 0
	s_lshl_b32 s22, s35, 2
	s_add_u32 s18, s18, s22
	s_addc_u32 s19, s19, 0
	s_add_u32 s78, s18, 0x118000
	v_readlane_b32 s18, v255, 3
	v_lshlrev_b32_e32 v4, 1, v116
	s_addc_u32 s79, s19, 0
	v_lshl_add_u32 v61, v235, 2, s18
	s_lshl_b32 s18, s37, 1
	v_and_b32_e32 v5, 14, v4
	v_lshrrev_b32_e32 v7, 2, v116
	s_add_u32 s18, s20, s18
	v_and_b32_e32 v52, 16, v7
	s_addc_u32 s19, s21, 0
	v_lshlrev_b32_e32 v16, 1, v5
	v_ashrrev_i32_e32 v87, 4, v116
	v_add_u32_e32 v64, 0, v4
	v_lshlrev_b32_e32 v67, 5, v5
	v_lshl_add_u64 v[4:5], s[18:19], 0, v[16:17]
	v_lshlrev_b32_e32 v16, 8, v52
	v_lshl_or_b32 v69, v139, 10, v16
	v_lshl_or_b32 v16, v87, 8, v122
	v_add_u32_e32 v92, 16, v87
	v_and_b32_e32 v60, 1, v116
	v_add_u32_e32 v91, 0, v16
	v_lshl_or_b32 v16, v92, 8, v122
	v_add_u32_e32 v93, 0, v16
	v_add_u32_e32 v16, 0x11200, v64
	v_cmp_eq_u32_e32 vcc, 0, v60
	v_or_b32_e32 v7, v52, v140
	v_mul_u32_u24_e32 v7, 0x90, v7
	v_cndmask_b32_e32 v98, v61, v16, vcc
	v_add_u32_e32 v16, 0x11000, v64
	v_cndmask_b32_e32 v99, v61, v16, vcc
	v_add_u32_e32 v16, 0x10e00, v64
	v_cndmask_b32_e32 v100, v61, v16, vcc
	v_add_u32_e32 v16, 0x10c00, v64
	v_cndmask_b32_e32 v101, v61, v16, vcc
	v_add_u32_e32 v16, 0x10a00, v64
	s_mov_b64 s[18:19], 0xe488000
	v_cndmask_b32_e32 v102, v61, v16, vcc
	v_add_u32_e32 v16, 0x10800, v64
	v_add3_u32 v62, 0, v6, v7
	v_or_b32_e32 v6, s38, v140
	v_lshl_add_u64 v[18:19], v[4:5], 0, s[18:19]
	s_mov_b32 s18, 0x5040100
	s_movk_i32 s20, 0xffde
	v_add_u32_e32 v97, v106, v105
	v_cndmask_b32_e32 v103, v61, v16, vcc
	v_add_u32_e32 v16, 0x10600, v64
	v_cmp_eq_u32_e64 s[16:17], 0, v6
	v_perm_b32 v7, v153, v151, s18
	v_perm_b32 v6, v149, v147, s18
	v_perm_b32 v5, v145, v143, s18
	v_perm_b32 v4, v142, v141, s18
	v_perm_b32 v11, v165, v163, s18
	v_perm_b32 v10, v162, v161, s18
	v_perm_b32 v9, v160, v159, s18
	v_perm_b32 v8, v158, v157, s18
	v_perm_b32 v15, v186, v184, s18
	v_perm_b32 v14, v182, v180, s18
	v_perm_b32 v13, v178, v176, s18
	v_perm_b32 v12, v174, v173, s18
	v_perm_b32 v27, v198, v195, s18
	v_perm_b32 v26, v194, v193, s18
	v_perm_b32 v25, v192, v191, s18
	v_perm_b32 v24, v190, v189, s18
	v_perm_b32 v35, v156, v155, s18
	v_perm_b32 v34, v154, v152, s18
	v_perm_b32 v33, v150, v148, s18
	v_perm_b32 v32, v146, v144, s18
	v_perm_b32 v39, v172, v171, s18
	v_perm_b32 v38, v170, v169, s18
	v_perm_b32 v37, v168, v167, s18
	v_perm_b32 v36, v166, v164, s18
	v_perm_b32 v43, v188, v187, s18
	v_perm_b32 v42, v185, v183, s18
	v_perm_b32 v41, v181, v179, s18
	v_perm_b32 v40, v177, v175, s18
	v_perm_b32 v47, v204, v203, s18
	v_perm_b32 v46, v202, v201, s18
	v_perm_b32 v45, v200, v199, s18
	v_perm_b32 v44, v197, v196, s18
	v_mad_u64_u32 v[58:59], s[18:19], v97, s20, v[104:105]
	v_cndmask_b32_e32 v104, v61, v16, vcc
	v_add_u32_e32 v16, 0x10400, v64
	v_cndmask_b32_e32 v105, v61, v16, vcc
	v_add_u32_e32 v16, 0x10200, v64
	v_cndmask_b32_e32 v106, v61, v16, vcc
	v_add_u32_e32 v16, 0x10000, v64
	v_cndmask_b32_e32 v107, v61, v16, vcc
	v_add_u32_e32 v16, 0xfe00, v64
	v_cndmask_b32_e32 v108, v61, v16, vcc
	v_add_u32_e32 v16, 0xfc00, v64
	v_cndmask_b32_e32 v109, v61, v16, vcc
	v_add_u32_e32 v16, 0xfa00, v64
	v_cndmask_b32_e32 v110, v61, v16, vcc
	v_add_u32_e32 v16, 0xf800, v64
	v_cndmask_b32_e32 v111, v61, v16, vcc
	v_add_u32_e32 v16, 0xf600, v64
	v_cndmask_b32_e32 v112, v61, v16, vcc
	v_add_u32_e32 v16, 0xf400, v64
	v_cndmask_b32_e32 v113, v61, v16, vcc
	v_add_u32_e32 v16, 0xf200, v64
	v_cndmask_b32_e32 v114, v61, v16, vcc
	v_add_u32_e32 v16, 0xf000, v64
	v_add_u32_e32 v94, v206, v205
	v_cndmask_b32_e32 v115, v61, v16, vcc
	v_add_u32_e32 v16, 0xee00, v64
	v_and_b32_e32 v63, 48, v116
	v_ashrrev_i32_e32 v90, 3, v116
	v_mad_u64_u32 v[52:53], s[18:19], v94, s20, v[116:117]
	v_cndmask_b32_e32 v116, v61, v16, vcc
	v_add_u32_e32 v16, 0xec00, v64
	v_add_u32_e32 v95, v234, v233
	v_cndmask_b32_e32 v122, v61, v16, vcc
	v_add_u32_e32 v16, 0xea00, v64
	v_mad_u64_u32 v[54:55], s[18:19], v95, s20, v[124:125]
	v_add_u32_e32 v96, v237, v236
	v_cndmask_b32_e32 v124, v61, v16, vcc
	v_add_u32_e32 v16, 0xe800, v64
	v_mad_u64_u32 v[56:57], s[18:19], v96, s20, v[126:127]
	v_cndmask_b32_e32 v126, v61, v16, vcc
	v_add_u32_e32 v16, 0xe600, v64
	v_lshl_add_u32 v88, v140, 4, 0
	v_cndmask_b32_e32 v139, v61, v16, vcc
	v_add_u32_e32 v16, 0xe400, v64
	v_mad_i32_i24 v68, v140, -12, v88
	v_cndmask_b32_e32 v140, v61, v16, vcc
	v_add_u32_e32 v16, 0xe200, v64
	v_cndmask_b32_e32 v141, v61, v16, vcc
	v_add_u32_e32 v16, 0xe000, v64
	v_cndmask_b32_e32 v142, v61, v16, vcc
	v_add_u32_e32 v16, 0xde00, v64
	v_cndmask_b32_e32 v143, v61, v16, vcc
	v_add_u32_e32 v16, 0xdc00, v64
	v_cndmask_b32_e32 v144, v61, v16, vcc
	v_add_u32_e32 v16, 0xda00, v64
	v_cndmask_b32_e32 v145, v61, v16, vcc
	v_add_u32_e32 v16, 0xd800, v64
	v_cndmask_b32_e32 v146, v61, v16, vcc
	v_add_u32_e32 v16, 0xd600, v64
	v_cndmask_b32_e32 v147, v61, v16, vcc
	v_and_b32_e32 v16, -16, v52
	v_add_u32_e32 v65, 0xd400, v64
	v_cmp_ne_u32_e64 s[18:19], 16, v16
	v_lshl_add_u32 v16, v94, 6, 0
	v_lshlrev_b32_e32 v53, 5, v52
	s_mov_b32 s28, 0x9c00
	s_movk_i32 s29, 0xc0
	s_movk_i32 s30, 0xff90
	v_cndmask_b32_e32 v148, v61, v65, vcc
	v_add3_u32 v55, v16, v53, s28
	v_mad_u64_u32 v[60:61], s[20:21], v94, s29, v[16:17]
	v_mul_lo_u32 v16, v94, s30
	v_lshlrev_b32_e32 v59, 4, v52
	v_add3_u32 v59, v60, v16, v59
	v_and_b32_e32 v16, -16, v54
	v_cmp_ne_u32_e64 s[20:21], 16, v16
	v_lshl_add_u32 v16, v95, 6, 0
	v_add_u32_e32 v53, v60, v53
	v_lshlrev_b32_e32 v64, 5, v54
	v_mad_u64_u32 v[60:61], s[22:23], v95, s29, v[16:17]
	v_add3_u32 v65, v16, v64, s28
	v_mul_lo_u32 v16, v95, s30
	v_lshlrev_b32_e32 v61, 4, v54
	v_add3_u32 v71, v60, v16, v61
	v_and_b32_e32 v16, -16, v56
	v_cmp_ne_u32_e64 s[22:23], 16, v16
	v_lshl_add_u32 v16, v96, 6, 0
	v_add_u32_e32 v64, v60, v64
	v_lshlrev_b32_e32 v72, 5, v56
	v_mad_u64_u32 v[60:61], s[24:25], v96, s29, v[16:17]
	v_add3_u32 v82, v16, v72, s28
	v_mul_lo_u32 v16, v96, s30
	v_lshlrev_b32_e32 v61, 4, v56
	v_add3_u32 v158, v60, v16, v61
	v_and_b32_e32 v16, -16, v58
	v_cmp_ne_u32_e64 s[24:25], 16, v16
	v_lshl_add_u32 v16, v97, 6, 0
	v_add_u32_e32 v83, v60, v72
	v_lshlrev_b32_e32 v72, 5, v58
	v_mad_u64_u32 v[60:61], s[26:27], v97, s29, v[16:17]
	v_add3_u32 v152, v16, v72, s28
	v_mul_lo_u32 v16, v97, s30
	v_lshlrev_b32_e32 v61, 4, v58
	v_add3_u32 v159, v60, v16, v61
	v_lshl_add_u32 v16, v86, 6, 0
	v_add_u32_e32 v153, v60, v72
	v_lshlrev_b32_e32 v72, 5, v84
	v_mad_u64_u32 v[60:61], s[26:27], v86, s29, v[16:17]
	v_add3_u32 v155, v16, v72, s28
	v_add_u32_e32 v16, v60, v72
	v_mul_lo_u32 v61, v86, s30
	v_lshlrev_b32_e32 v72, 4, v84
	v_mov_b32_e32 v149, s40
	v_mov_b32_e32 v150, s41
	v_cmp_gt_u32_e64 s[26:27], 32, v52
	v_add3_u32 v160, v60, v61, v72
	v_mov_b32_e32 v80, s42
	v_mov_b32_e32 v81, s34
	v_cmp_gt_i32_e32 vcc, 8, v52
	v_cndmask_b32_e64 v61, v149, v150, s[26:27]
	v_mov_b32_e32 v151, s39
	v_cmp_gt_u32_e64 s[26:27], 24, v52
	v_cndmask_b32_e32 v60, v80, v81, vcc
	v_cmp_gt_i32_e64 s[28:29], 16, v52
	v_cndmask_b32_e64 v61, v61, v151, s[26:27]
	v_cmp_gt_u32_e64 s[30:31], 32, v54
	v_cndmask_b32_e64 v60, v61, v60, s[28:29]
	v_lshl_add_u32 v60, v52, 3, v60
	v_ashrrev_i32_e32 v61, 31, v60
	v_lshl_add_u64 v[72:73], v[60:61], 1, s[58:59]
	v_cmp_gt_i32_e64 s[28:29], 8, v54
	v_cndmask_b32_e64 v61, v149, v150, s[30:31]
	v_cmp_gt_u32_e64 s[30:31], 24, v54
	v_cndmask_b32_e64 v60, v80, v81, s[28:29]
	v_cmp_gt_i32_e64 s[34:35], 16, v54
	v_cndmask_b32_e64 v61, v61, v151, s[30:31]
	v_cmp_gt_u32_e64 s[36:37], 32, v56
	v_cndmask_b32_e64 v60, v61, v60, s[34:35]
	v_lshl_add_u32 v60, v54, 3, v60
	v_ashrrev_i32_e32 v61, 31, v60
	v_lshl_add_u64 v[74:75], v[60:61], 1, s[58:59]
	v_cmp_gt_i32_e64 s[34:35], 8, v56
	v_cndmask_b32_e64 v61, v149, v150, s[36:37]
	v_cmp_gt_u32_e64 s[36:37], 24, v56
	v_cndmask_b32_e64 v60, v80, v81, s[34:35]
	v_cmp_gt_i32_e64 s[38:39], 16, v56
	v_cndmask_b32_e64 v61, v61, v151, s[36:37]
	v_cmp_gt_u32_e64 s[40:41], 32, v58
	v_cndmask_b32_e64 v60, v61, v60, s[38:39]
	v_lshl_add_u32 v60, v56, 3, v60
	v_ashrrev_i32_e32 v61, 31, v60
	v_lshl_add_u64 v[76:77], v[60:61], 1, s[58:59]
	v_cmp_gt_i32_e64 s[38:39], 8, v58
	v_cndmask_b32_e64 v61, v149, v150, s[40:41]
	v_cmp_gt_u32_e64 s[40:41], 24, v58
	v_cndmask_b32_e64 v60, v80, v81, s[38:39]
	v_cmp_gt_i32_e64 s[42:43], 16, v58
	v_cndmask_b32_e64 v61, v61, v151, s[40:41]
	v_cmp_gt_u32_e64 s[44:45], 32, v84
	v_cndmask_b32_e64 v60, v61, v60, s[42:43]
	v_lshl_add_u32 v60, v58, 3, v60
	v_ashrrev_i32_e32 v61, 31, v60
	v_lshl_add_u64 v[78:79], v[60:61], 1, s[58:59]
	v_cmp_gt_i32_e64 s[42:43], 8, v84
	v_cndmask_b32_e64 v61, v149, v150, s[44:45]
	v_cmp_gt_u32_e64 s[44:45], 24, v84
	v_cndmask_b32_e64 v60, v80, v81, s[42:43]
	v_cmp_gt_i32_e64 s[48:49], 16, v84
	v_cndmask_b32_e64 v61, v61, v151, s[44:45]
	v_add_u32_e32 v57, 0x1f00, v53
	v_cndmask_b32_e64 v60, v61, v60, s[48:49]
	v_cmp_gt_u32_e64 s[48:49], 16, v52
	v_add_u32_e32 v70, 0x1f00, v64
	v_add_u32_e32 v85, 0x1f00, v83
	v_cndmask_b32_e64 v52, v55, v57, s[48:49]
	v_cndmask_b32_e32 v149, v52, v53, vcc
	v_cmp_gt_u32_e32 vcc, 16, v54
	v_add_u32_e32 v154, 0x1f00, v153
	v_add_u32_e32 v156, 0x1f00, v16
	v_cndmask_b32_e32 v53, v65, v70, vcc
	v_cmp_gt_u32_e32 vcc, 16, v56
	v_lshl_add_u32 v60, v84, 3, v60
	v_mov_b32_e32 v57, 0xc080
	v_cndmask_b32_e32 v54, v82, v85, vcc
	v_cmp_gt_u32_e32 vcc, 16, v58
	v_lshl_add_u32 v66, v90, 9, 0
	v_ashrrev_i32_e32 v61, 31, v60
	v_cndmask_b32_e32 v55, v152, v154, vcc
	v_cmp_gt_u32_e32 vcc, 16, v84
	v_cndmask_b32_e64 v52, v57, v254, s[26:27]
	v_cndmask_b32_e64 v150, v53, v64, s[28:29]
	v_cndmask_b32_e32 v56, v155, v156, vcc
	v_cndmask_b32_e64 v53, v57, v254, s[30:31]
	v_cndmask_b32_e64 v151, v54, v83, s[34:35]
	v_cndmask_b32_e64 v54, v57, v254, s[36:37]
	v_cndmask_b32_e64 v152, v55, v153, s[38:39]
	v_cndmask_b32_e64 v55, v57, v254, s[40:41]
	v_cndmask_b32_e64 v153, v56, v16, s[42:43]
	v_cndmask_b32_e64 v56, v57, v254, s[44:45]
	v_mov_b32_e32 v16, v17
	v_lshl_add_u32 v89, v87, 2, 0
	v_lshl_add_u64 v[80:81], v[60:61], 1, s[58:59]
	s_mov_b32 s34, -8
	v_add_u32_e32 v154, v62, v63
	v_add_u32_e32 v155, v66, v67
	v_add_u32_e32 v156, v59, v52
	v_add_u32_e32 v157, v71, v53
	v_add_u32_e32 v158, v158, v54
	v_add_u32_e32 v159, v159, v55
	v_add_u32_e32 v160, v160, v56
	v_add_u32_e32 v161, v68, v69
	v_mov_b64_e32 v[82:83], v[16:17]
	v_mov_b64_e32 v[84:85], v[16:17]
	v_mov_b32_e32 v52, v232
	v_mov_b32_e32 v53, v231
	v_mov_b32_e32 v54, v230
	v_mov_b32_e32 v55, v207
	s_waitcnt lgkmcnt(0)
	s_barrier
	v_mad_u64_u32 v[218:219], s[26:27], v94, s83, v[72:73]
	v_mad_u64_u32 v[220:221], s[26:27], v95, s83, v[74:75]
	v_mad_u64_u32 v[222:223], s[26:27], v96, s83, v[76:77]
	v_mad_u64_u32 v[244:245], s[26:27], v97, s83, v[78:79]
	v_mad_u64_u32 v[246:247], s[26:27], v86, s83, v[80:81]
	v_and_b32_e32 v98, 31, v119
	v_lshlrev_b32_e32 v98, 3, v98
	v_lshrrev_b32_e32 v99, 5, v119
	s_lshl_b32 s26, s32, 3
	v_add_u32_e32 v99, s26, v99
	v_lshl_add_u32 v99, v99, 2, v228
	v_add_u32_e32 v99, 0x6000, v99
	v_lshrrev_b32_e32 v100, 1, v119
	v_lshlrev_b32_e32 v100, 2, v100
	v_add_u32_e32 v100, 0xd400, v100
	v_lshrrev_b32_e32 v101, 3, v119
	v_lshlrev_b32_e32 v101, 9, v101
	v_and_b32_e32 v102, 7, v119
	v_lshl_add_u32 v101, v102, 6, v101
	v_add_u32_e32 v101, 0xd400, v101
	v_sub_u32_e32 v102, s26, v102
	v_lshlrev_b32_e32 v102, 1, v102
	v_ashrrev_i32_e32 v103, 31, v102
	v_lshl_add_u64 v[102:103], v[18:19], 0, v[102:103]
	s_load_dwordx2 s[26:27], s[84:85], 0x120
	v_lshrrev_b32_e32 v60, 3, v119
	v_and_b32_e32 v61, 7, v119
	v_mov_b32_e32 v62, s82
	v_add_u32_e32 v62, 0xffffff80, v62
	v_bfe_u32 v63, v62, 2, 3
	v_lshlrev_b32_e32 v63, 6, v63
	v_lshrrev_b32_e32 v64, 5, v62
	v_lshlrev_b32_e32 v64, 6, v64
	v_and_b32_e32 v65, 3, v62
	v_lshlrev_b32_e32 v65, 4, v65
	v_lshl_add_u32 v66, v61, 3, v63
	v_lshl_add_u32 v67, v61, 3, v64
	v_add_u32_e32 v67, 0x600, v67
	v_and_b32_e32 v68, 1, v119
	v_lshl_add_u32 v69, v68, 3, v63
	v_add_u32_e32 v69, v69, v65
	v_add_u32_e32 v69, 0x400, v69
	v_mul_u32_u24_e32 v70, 0x1200, v60
	v_lshrrev_b32_e32 v71, 1, v119
	v_mul_u32_u24_e32 v162, 0x1200, v71
	s_waitcnt lgkmcnt(0)
	s_add_u32 s26, s26, 0x6aa8000
	s_addc_u32 s27, s27, 0
	v_lshl_add_u32 v16, v66, 1, v70
	v_lshl_add_u64 v[218:219], v[16:17], 0, s[26:27]
	v_add_u32_e32 v16, 0x400, v16
	v_lshl_add_u64 v[220:221], v[16:17], 0, s[26:27]
	v_lshl_add_u32 v16, v67, 1, v70
	v_lshl_add_u64 v[222:223], v[16:17], 0, s[26:27]
	v_add_u32_e32 v16, 0x100, v16
	v_lshl_add_u64 v[244:245], v[16:17], 0, s[26:27]
	v_lshl_add_u32 v16, v69, 1, v162
	v_lshl_add_u64 v[246:247], v[16:17], 0, s[26:27]
	v_lshlrev_b32_e32 v149, 8, v60
	v_lshl_add_u32 v149, v61, 5, v149
	v_add_u32_e32 v150, 0x2000, v149
	v_mul_u32_u24_e32 v156, 0x90, v60
	v_lshl_add_u32 v156, v61, 4, v156
	v_add_u32_e32 v156, 0xb000, v156
	v_add_u32_e32 v157, 0x1200, v156
	v_lshlrev_b32_e32 v151, 6, v71
	v_lshl_add_u32 v151, v68, 5, v151
	v_add_u32_e32 v151, 0xa000, v151
	v_mul_f32_e32 v117, s73, v117
	v_mul_f32_e32 v121, s73, v121
	v_mul_f32_e32 v123, s73, v123
	v_mul_f32_e32 v125, s73, v125
	v_add_u32_e32 v153, 0x100, v98
	v_add_u32_e32 v159, 0x400, v99
	v_add_u32_e32 v160, 0x800, v98
	v_add_u32_e32 v230, 0x1000, v98
	v_add_u32_e32 v231, 0x1800, v98
	v_add_u32_e32 v152, 0x8000, v161
	v_add_u32_e32 v158, 0x4000, v161
	v_and_b32_e32 v60, 15, v119
	v_mul_u32_u24_e32 v61, 12, v60
	v_add_u32_e32 v91, v91, v61
	v_add_u32_e32 v93, v93, v61
	v_readlane_b32 s26, v255, 18
	s_lshl_b32 s26, s26, 9
	v_mov_b32_e32 v62, s82
	v_add_u32_e32 v62, 0xffffff80, v62
	v_bfe_u32 v62, v62, 2, 3
	v_lshlrev_b32_e32 v62, 6, v62
	v_add_u32_e32 v62, s26, v62
	v_lshl_add_u32 v62, v60, 2, v62
	v_lshlrev_b32_e32 v16, 2, v62
	s_load_dwordx2 s[26:27], s[84:85], 0x78
	s_waitcnt lgkmcnt(0)
	global_load_dword v127, v16, s[26:27]
	global_load_dword v130, v16, s[26:27] offset:4
	global_load_dword v133, v16, s[26:27] offset:8
	global_load_dword v136, v16, s[26:27] offset:12
	s_load_dwordx2 s[26:27], s[84:85], 0x80
	s_waitcnt lgkmcnt(0)
	global_load_dword v128, v16, s[26:27]
	global_load_dword v131, v16, s[26:27] offset:4
	global_load_dword v134, v16, s[26:27] offset:8
	global_load_dword v137, v16, s[26:27] offset:12
	s_load_dwordx2 s[26:27], s[84:85], 0x88
	s_waitcnt lgkmcnt(0)
	global_load_dword v129, v16, s[26:27]
	global_load_dword v132, v16, s[26:27] offset:4
	global_load_dword v135, v16, s[26:27] offset:8
	global_load_dword v138, v16, s[26:27] offset:12
	s_waitcnt vmcnt(0)
	s_branch .LBB0_424

.Lrb_done:
	v_add_u32_e32 v64, 0x8000, v91
	v_add_co_u32_e64 v16, s[26:27], s34, 8
	s_waitcnt lgkmcnt(0)
	s_barrier
	v_add_u32_e32 v56, 0x2000, v91
	v_add_u32_e32 v57, 0x8000, v91
	v_add_u32_e32 v58, 0x6000, v91
	v_add_u32_e32 v59, 0x2000, v93
	v_add_u32_e32 v60, 0x8000, v93
	v_add_u32_e32 v61, 0x6000, v93
	ds_read_b128 v[170:173], v57
	ds_read_b128 v[174:177], v56
	ds_read_b128 v[178:181], v91
	ds_read_b128 v[186:189], v60
	ds_read_b128 v[190:193], v59
	ds_read_b128 v[194:197], v93
	v_readfirstlane_b32 s30, v16
	s_and_b64 s[28:29], s[26:27], exec
	s_cselect_b32 s28, s30, s34
	s_cselect_b32 s29, 7, 0x1ff
	s_sub_i32 s29, s29, s28
	s_and_b64 s[26:27], s[26:27], exec
	s_cselect_b32 s31, 0x4000, 0
	s_and_b64 s[26:27], s[64:65], exec
	s_cselect_b32 s26, s28, s29
	s_lshl_b32 s35, s26, 5
	s_add_i32 s35, s35, s31
	s_waitcnt lgkmcnt(3)
	v_add_f32_e32 v206, -1.0, v170
	v_mul_f32_e32 v182, v127, v174
	v_fma_f32 v206, v128, v206, 1.0
	v_mul_f32_e32 v202, v182, v182
	v_mul_f32_e32 v174, v174, v206
	v_mul_f32_e32 v178, v178, v174
	v_mul_f32_e32 v204, v129, v178
	v_add_f32_e32 v206, -1.0, v171
	v_mul_f32_e32 v183, v130, v175
	v_fma_f32 v206, v131, v206, 1.0
	v_fmac_f32_e32 v202, v183, v183
	v_mul_f32_e32 v175, v175, v206
	v_mul_f32_e32 v179, v179, v175
	v_fmac_f32_e32 v204, v132, v179
	v_add_f32_e32 v206, -1.0, v172
	v_mul_f32_e32 v184, v133, v176
	v_fma_f32 v206, v134, v206, 1.0
	v_fmac_f32_e32 v202, v184, v184
	v_mul_f32_e32 v176, v176, v206
	v_mul_f32_e32 v180, v180, v176
	v_fmac_f32_e32 v204, v135, v180
	v_add_f32_e32 v206, -1.0, v173
	v_mul_f32_e32 v185, v136, v177
	v_fma_f32 v206, v137, v206, 1.0
	v_fmac_f32_e32 v202, v185, v185
	v_mul_f32_e32 v177, v177, v206
	v_mul_f32_e32 v181, v181, v177
	v_fmac_f32_e32 v204, v138, v181
	ds_write_b128 v56, v[174:177]
	s_waitcnt lgkmcnt(1)
	v_add_f32_e32 v207, -1.0, v186
	v_mul_f32_e32 v198, v127, v190
	v_fma_f32 v207, v128, v207, 1.0
	v_mul_f32_e32 v203, v198, v198
	v_mul_f32_e32 v190, v190, v207
	v_mul_f32_e32 v194, v194, v190
	v_mul_f32_e32 v205, v129, v194
	v_add_f32_e32 v207, -1.0, v187
	v_mul_f32_e32 v199, v130, v191
	v_fma_f32 v207, v131, v207, 1.0
	v_fmac_f32_e32 v203, v199, v199
	v_mul_f32_e32 v191, v191, v207
	v_mul_f32_e32 v195, v195, v191
	v_fmac_f32_e32 v205, v132, v195
	v_add_f32_e32 v207, -1.0, v188
	v_mul_f32_e32 v200, v133, v192
	v_fma_f32 v207, v134, v207, 1.0
	v_fmac_f32_e32 v203, v200, v200
	v_mul_f32_e32 v192, v192, v207
	v_mul_f32_e32 v196, v196, v192
	v_fmac_f32_e32 v205, v135, v196
	v_add_f32_e32 v207, -1.0, v189
	v_mul_f32_e32 v201, v136, v193
	v_fma_f32 v207, v137, v207, 1.0
	v_fmac_f32_e32 v203, v201, v201
	v_mul_f32_e32 v193, v193, v207
	v_mul_f32_e32 v197, v197, v193
	v_fmac_f32_e32 v205, v138, v197
	ds_write_b128 v59, v[190:193]
	s_nop 1
	v_add_f32_dpp v202, v202, v202 quad_perm:[1,0,3,2] row_mask:0xf bank_mask:0xf bound_ctrl:1
	v_add_f32_dpp v203, v203, v203 quad_perm:[1,0,3,2] row_mask:0xf bank_mask:0xf bound_ctrl:1
	v_add_f32_dpp v204, v204, v204 quad_perm:[1,0,3,2] row_mask:0xf bank_mask:0xf bound_ctrl:1
	v_add_f32_dpp v205, v205, v205 quad_perm:[1,0,3,2] row_mask:0xf bank_mask:0xf bound_ctrl:1
	v_add_f32_dpp v202, v202, v202 quad_perm:[2,3,0,1] row_mask:0xf bank_mask:0xf bound_ctrl:1
	v_add_f32_dpp v203, v203, v203 quad_perm:[2,3,0,1] row_mask:0xf bank_mask:0xf bound_ctrl:1
	v_add_f32_dpp v204, v204, v204 quad_perm:[2,3,0,1] row_mask:0xf bank_mask:0xf bound_ctrl:1
	v_add_f32_dpp v205, v205, v205 quad_perm:[2,3,0,1] row_mask:0xf bank_mask:0xf bound_ctrl:1
	v_add_f32_dpp v202, v202, v202 row_half_mirror row_mask:0xf bank_mask:0xf bound_ctrl:1
	v_add_f32_dpp v203, v203, v203 row_half_mirror row_mask:0xf bank_mask:0xf bound_ctrl:1
	v_add_f32_dpp v204, v204, v204 row_half_mirror row_mask:0xf bank_mask:0xf bound_ctrl:1
	v_add_f32_dpp v205, v205, v205 row_half_mirror row_mask:0xf bank_mask:0xf bound_ctrl:1
	v_add_f32_dpp v202, v202, v202 row_mirror row_mask:0xf bank_mask:0xf bound_ctrl:1
	v_add_f32_dpp v203, v203, v203 row_mirror row_mask:0xf bank_mask:0xf bound_ctrl:1
	v_add_f32_dpp v204, v204, v204 row_mirror row_mask:0xf bank_mask:0xf bound_ctrl:1
	v_add_f32_dpp v205, v205, v205 row_mirror row_mask:0xf bank_mask:0xf bound_ctrl:1
	v_sqrt_f32_e32 v202, v202
	v_sqrt_f32_e32 v203, v203
	s_nop 0
	v_max_f32_e32 v202, 0x2b8cbccc, v202
	v_max_f32_e32 v203, 0x2b8cbccc, v203
	v_rcp_f32_e32 v202, v202
	v_rcp_f32_e32 v203, v203
	s_nop 0
	v_mul_f32_e32 v182, v182, v202
	v_mul_f32_e32 v183, v183, v202
	v_mul_f32_e32 v184, v184, v202
	v_mul_f32_e32 v185, v185, v202
	v_mul_f32_e32 v170, v170, v182
	v_mul_f32_e32 v171, v171, v183
	v_mul_f32_e32 v172, v172, v184
	v_mul_f32_e32 v173, v173, v185
	ds_write_b128 v58, v[182:185]
	ds_write_b128 v57, v[170:173]
	v_mul_f32_e32 v198, v198, v203
	v_mul_f32_e32 v199, v199, v203
	v_mul_f32_e32 v200, v200, v203
	v_mul_f32_e32 v201, v201, v203
	v_mul_f32_e32 v186, v186, v198
	v_mul_f32_e32 v187, v187, v199
	v_mul_f32_e32 v188, v188, v200
	v_mul_f32_e32 v189, v189, v201
	ds_write_b128 v61, v[198:201]
	ds_write_b128 v60, v[186:189]
	s_and_saveexec_b64 s[26:27], s[16:17]
	s_cbranch_execz .LBB0_492
	v_add_u32_e32 v62, s35, v87
	v_ashrrev_i32_e32 v63, 31, v62
	v_lshlrev_b64 v[62:63], 5, v[62:63]
	v_lshl_add_u64 v[62:63], s[78:79], 0, v[62:63]
	global_store_dword v[62:63], v204, off
	v_add_u32_e32 v62, s35, v92
	v_ashrrev_i32_e32 v63, 31, v62
	v_lshlrev_b64 v[62:63], 5, v[62:63]
	v_lshl_add_u64 v[62:63], s[78:79], 0, v[62:63]
	global_store_dword v[62:63], v205, off
